# unit prologues: banded-attention bias-table load overlapped with the K/V DMA issue (counted vmcnt); MLA wave-0 extra wait and dead copies removed
# baseline (speedup 1.0000x reference)
.LBB0_471:
	s_or_b64 exec, exec, s[38:39]
	s_lshl_b32 s5, s5, 10
	s_add_i32 s13, s5, 0
	s_mov_b32 m0, s13
	v_lshl_add_u64 v[32:33], v[6:7], 0, v[134:135]
	global_load_lds_dwordx4 v[6:7], off
	s_add_i32 m0, s13, 0x2000
	v_lshl_add_u64 v[34:35], v[28:29], 0, v[136:137]
	global_load_lds_dwordx4 v[28:29], off
	s_add_i32 m0, s13, 0x4000
	s_cmp_lt_u32 s7, 64
	global_load_lds_dwordx4 v[30:31], off
	s_cselect_b64 s[16:17], -1, 0
	s_cmp_gt_u32 s7, 63
	v_lshl_add_u64 v[28:29], v[30:31], 0, v[138:139]
	s_cbranch_scc1 .LBB0_473
	s_add_i32 m0, 0, 0x6000
	v_lshl_add_u64 v[6:7], v[72:73], 0, v[140:141]
	global_load_lds_dwordx4 v[72:73], off
	v_mov_b64_e32 v[72:73], v[6:7]
	s_branch .LBB0_474
